# v92 + nt on the read-once SC loads of the conv-merge epilogue
# baseline (speedup 1.0000x reference)
.LBB0_624:
	s_and_b32 s2, 0xffff, s22
	v_lshl_add_u32 v144, s83, 8, v132
	s_lshl_b32 s2, s2, 8
	v_add_u32_e32 v146, 0xb0, v144
	v_mov_b32_e32 v147, 0
	s_or_b32 s2, s2, s27
	v_lshlrev_b64 v[128:129], 10, v[146:147]
	v_or_b32_e32 v146, s2, v236
	v_lshl_add_u64 v[128:129], v[128:129], 0, v[146:147]
	v_lshlrev_b64 v[128:129], 1, v[128:129]
	v_or_b32_e32 v130, 0x100, v128
	v_mov_b32_e32 v131, v129
	v_lshl_add_u64 v[132:133], s[6:7], 0, v[130:131]
	v_lshl_add_u64 v[130:131], s[70:71], 0, v[130:131]
	global_load_dwordx4 v[136:139], v[132:133], off
	global_load_dwordx4 v[140:143], v[130:131], off nt
	v_lshl_add_u64 v[130:131], s[6:7], 0, v[128:129]
	v_lshl_add_u64 v[132:133], s[70:71], 0, v[128:129]
	global_load_dwordx4 v[128:131], v[130:131], off
	s_nop 0
	global_load_dwordx4 v[132:135], v[132:133], off nt
	s_waitcnt vmcnt(0)
	v_lshlrev_b32_e32 v145, 16, v138
	v_lshlrev_b32_e32 v148, 16, v142
	v_and_b32_e32 v142, 0xffff0000, v142
	v_and_b32_e32 v138, 0xffff0000, v138
	v_lshlrev_b32_e32 v149, 16, v139
	v_and_b32_e32 v139, 0xffff0000, v139
	v_mul_f32_e32 v145, 0xbfb8aa3b, v145
	v_mul_f32_e32 v148, 0xbfb8aa3b, v148
	v_mul_f32_e32 v142, 0xbfb8aa3b, v142
	v_lshlrev_b32_e32 v150, 16, v143
	v_and_b32_e32 v143, 0xffff0000, v143
	v_mul_f32_e32 v138, 0xbfb8aa3b, v138
	v_mul_f32_e32 v139, 0xbfb8aa3b, v139
	v_exp_f32_e32 v145, v145
	v_exp_f32_e32 v148, v148
	v_exp_f32_e32 v142, v142
	v_lshlrev_b32_e32 v153, 16, v137
	v_lshlrev_b32_e32 v154, 16, v141
	v_and_b32_e32 v137, 0xffff0000, v137
	v_and_b32_e32 v141, 0xffff0000, v141
	v_mul_f32_e32 v150, 0xbfb8aa3b, v150
	v_mul_f32_e32 v143, 0xbfb8aa3b, v143
	v_exp_f32_e32 v138, v138
	v_exp_f32_e32 v139, v139
	v_lshlrev_b32_e32 v151, 16, v136
	v_and_b32_e32 v136, 0xffff0000, v136
	v_mul_f32_e32 v154, 0xbfb8aa3b, v154
	v_mul_f32_e32 v137, 0xbfb8aa3b, v137
	v_mul_f32_e32 v141, 0xbfb8aa3b, v141
	v_exp_f32_e32 v150, v150
	v_exp_f32_e32 v143, v143
	v_mul_f32_e32 v136, 0xbfb8aa3b, v136
	v_exp_f32_e32 v154, v154
	v_exp_f32_e32 v156, v137
	v_exp_f32_e32 v137, v141
	v_lshlrev_b32_e32 v152, 16, v140
	v_and_b32_e32 v140, 0xffff0000, v140
	v_mul_f32_e32 v149, 0xbfb8aa3b, v149
	v_exp_f32_e32 v136, v136
	v_add_f32_e32 v141, 1.0, v145
	v_add_f32_e32 v145, 1.0, v148
	v_add_f32_e32 v142, 1.0, v142
	v_mul_f32_e32 v152, 0xbfb8aa3b, v152
	v_mul_f32_e32 v140, 0xbfb8aa3b, v140
	v_mul_f32_e32 v153, 0xbfb8aa3b, v153
	v_exp_f32_e32 v149, v149
	v_add_f32_e32 v148, 1.0, v138
	v_add_f32_e32 v155, 1.0, v139
	v_rcp_f32_e32 v138, v145
	v_rcp_f32_e32 v139, v142
	v_exp_f32_e32 v152, v152
	v_exp_f32_e32 v140, v140
	v_exp_f32_e32 v153, v153
	v_add_f32_e32 v150, 1.0, v150
	v_add_f32_e32 v143, 1.0, v143
	v_add_f32_e32 v154, 1.0, v154
	v_add_f32_e32 v159, 1.0, v137
	v_rcp_f32_e32 v142, v150
	v_rcp_f32_e32 v143, v143
	v_mul_f32_e32 v151, 0xbfb8aa3b, v151
	v_add_f32_e32 v157, 1.0, v136
	v_min_f32_e32 v136, 0x7149f2ca, v141
	v_min_f32_e32 v137, 0x7149f2ca, v148
	v_min_f32_e32 v141, 0x7149f2ca, v155
	v_rcp_f32_e32 v154, v154
	v_rcp_f32_e32 v155, v159
	v_exp_f32_e32 v151, v151
	v_add_f32_e32 v149, 1.0, v149
	v_pk_mul_f32 v[136:137], v[136:137], v[138:139]
	v_add_f32_e32 v152, 1.0, v152
	v_add_f32_e32 v158, 1.0, v140
	v_add_f32_e32 v153, 1.0, v153
	v_min_f32_e32 v140, 0x7149f2ca, v149
	v_pk_mul_f32 v[0:1], v[0:1], v[136:137]
	v_add_f32_e32 v136, 1.0, v156
	v_rcp_f32_e32 v150, v152
	v_min_f32_e32 v152, 0x7149f2ca, v153
	v_pk_mul_f32 v[138:139], v[140:141], v[142:143]
	v_min_f32_e32 v153, 0x7149f2ca, v136
	v_pk_mul_f32 v[2:3], v[2:3], v[138:139]
	v_pk_mul_f32 v[138:139], v[152:153], v[154:155]
	v_add_f32_e32 v151, 1.0, v151
	v_pk_mul_f32 v[6:7], v[6:7], v[138:139]
	v_lshlrev_b32_e32 v138, 16, v130
	v_min_f32_e32 v148, 0x7149f2ca, v151
	v_rcp_f32_e32 v151, v158
	v_mul_f32_e32 v138, 0xbfb8aa3b, v138
	v_exp_f32_e32 v138, v138
	v_min_f32_e32 v149, 0x7149f2ca, v157
	v_pk_mul_f32 v[136:137], v[148:149], v[150:151]
	v_lshlrev_b32_e32 v139, 16, v134
	v_pk_mul_f32 v[4:5], v[4:5], v[136:137]
	v_add_f32_e32 v136, 1.0, v138
	v_min_f32_e32 v148, 0x7149f2ca, v136
	v_add_u32_e32 v136, 0xa0, v144
	v_mov_b32_e32 v137, v147
	v_mul_f32_e32 v139, 0xbfb8aa3b, v139
	v_lshlrev_b64 v[136:137], 10, v[136:137]
	v_exp_f32_e32 v139, v139
	v_lshl_add_u64 v[136:137], v[136:137], 0, v[146:147]
	v_lshlrev_b64 v[150:151], 1, v[136:137]
	v_or_b32_e32 v140, 0x100, v150
	v_mov_b32_e32 v141, v151
	v_lshl_add_u64 v[136:137], s[6:7], 0, v[140:141]
	v_add_f32_e32 v145, 1.0, v139
	global_load_dwordx4 v[136:139], v[136:137], off
	v_lshl_add_u64 v[140:141], s[70:71], 0, v[140:141]
	global_load_dwordx4 v[140:143], v[140:141], off nt
	v_and_b32_e32 v130, 0xffff0000, v130
	v_mul_f32_e32 v130, 0xbfb8aa3b, v130
	v_and_b32_e32 v134, 0xffff0000, v134
	v_exp_f32_e32 v130, v130
	v_mul_f32_e32 v134, 0xbfb8aa3b, v134
	v_exp_f32_e32 v134, v134
	v_rcp_f32_e32 v152, v145
	v_add_f32_e32 v130, 1.0, v130
	v_min_f32_e32 v149, 0x7149f2ca, v130
	v_add_f32_e32 v130, 1.0, v134
	v_lshlrev_b32_e32 v134, 16, v131
	v_lshlrev_b32_e32 v145, 16, v135
	v_and_b32_e32 v135, 0xffff0000, v135
	v_mul_f32_e32 v134, 0xbfb8aa3b, v134
	v_mul_f32_e32 v145, 0xbfb8aa3b, v145
	v_mul_f32_e32 v135, 0xbfb8aa3b, v135
	v_exp_f32_e32 v134, v134
	v_exp_f32_e32 v145, v145
	v_exp_f32_e32 v135, v135
	v_and_b32_e32 v131, 0xffff0000, v131
	v_mul_f32_e32 v131, 0xbfb8aa3b, v131
	v_exp_f32_e32 v131, v131
	v_rcp_f32_e32 v153, v130
	v_add_f32_e32 v130, 1.0, v134
	v_add_f32_e32 v134, 1.0, v145
	v_add_f32_e32 v135, 1.0, v135
	v_rcp_f32_e32 v134, v134
	v_rcp_f32_e32 v135, v135
	v_add_f32_e32 v131, 1.0, v131
	v_min_f32_e32 v130, 0x7149f2ca, v130
	v_min_f32_e32 v131, 0x7149f2ca, v131
	v_pk_mul_f32 v[130:131], v[130:131], v[134:135]
	v_lshlrev_b32_e32 v135, 16, v133
	v_pk_mul_f32 v[10:11], v[10:11], v[130:131]
	v_lshlrev_b32_e32 v130, 16, v128
	v_lshlrev_b32_e32 v131, 16, v132
	v_and_b32_e32 v128, 0xffff0000, v128
	v_mul_f32_e32 v131, 0xbfb8aa3b, v131
	v_mul_f32_e32 v128, 0xbfb8aa3b, v128
	v_and_b32_e32 v132, 0xffff0000, v132
	v_exp_f32_e32 v131, v131
	v_exp_f32_e32 v128, v128
	v_mul_f32_e32 v132, 0xbfb8aa3b, v132
	v_exp_f32_e32 v132, v132
	v_add_f32_e32 v131, 1.0, v131
	v_add_f32_e32 v128, 1.0, v128
	v_rcp_f32_e32 v134, v131
	v_min_f32_e32 v131, 0x7149f2ca, v128
	v_add_f32_e32 v128, 1.0, v132
	v_lshlrev_b32_e32 v132, 16, v129
	v_and_b32_e32 v133, 0xffff0000, v133
	v_mul_f32_e32 v132, 0xbfb8aa3b, v132
	v_mul_f32_e32 v135, 0xbfb8aa3b, v135
	v_mul_f32_e32 v133, 0xbfb8aa3b, v133
	v_exp_f32_e32 v132, v132
	v_exp_f32_e32 v145, v135
	v_exp_f32_e32 v133, v133
	v_and_b32_e32 v129, 0xffff0000, v129
	v_mul_f32_e32 v129, 0xbfb8aa3b, v129
	v_exp_f32_e32 v129, v129
	v_rcp_f32_e32 v135, v128
	v_add_f32_e32 v128, 1.0, v132
	v_add_f32_e32 v132, 1.0, v145
	v_add_f32_e32 v133, 1.0, v133
	v_rcp_f32_e32 v132, v132
	v_rcp_f32_e32 v133, v133
	v_add_f32_e32 v129, 1.0, v129
	v_min_f32_e32 v128, 0x7149f2ca, v128
	v_min_f32_e32 v129, 0x7149f2ca, v129
	v_pk_mul_f32 v[128:129], v[128:129], v[132:133]
	v_mul_f32_e32 v130, 0xbfb8aa3b, v130
	v_pk_mul_f32 v[14:15], v[14:15], v[128:129]
	v_exp_f32_e32 v130, v130
	v_pk_mul_f32 v[148:149], v[148:149], v[152:153]
	v_add_f32_e32 v130, 1.0, v130
	s_waitcnt vmcnt(1)
	v_lshlrev_b32_e32 v128, 16, v138
	v_mul_f32_e32 v128, 0xbfb8aa3b, v128
	s_waitcnt vmcnt(0)
	v_lshlrev_b32_e32 v129, 16, v142
	v_exp_f32_e32 v128, v128
	v_mul_f32_e32 v129, 0xbfb8aa3b, v129
	v_exp_f32_e32 v129, v129
	v_min_f32_e32 v130, 0x7149f2ca, v130
	v_add_f32_e32 v128, 1.0, v128
	v_pk_mul_f32 v[8:9], v[8:9], v[148:149]
	v_pk_mul_f32 v[130:131], v[130:131], v[134:135]
	v_min_f32_e32 v148, 0x7149f2ca, v128
	v_add_f32_e32 v145, 1.0, v129
	v_and_b32_e32 v132, 0xffff0000, v138
	v_lshl_add_u64 v[128:129], s[6:7], 0, v[150:151]
	v_pk_mul_f32 v[12:13], v[12:13], v[130:131]
	global_load_dwordx4 v[128:131], v[128:129], off
	v_mul_f32_e32 v138, 0xbfb8aa3b, v132
	v_lshl_add_u64 v[132:133], s[70:71], 0, v[150:151]
	global_load_dwordx4 v[132:135], v[132:133], off nt
	v_and_b32_e32 v142, 0xffff0000, v142
	v_exp_f32_e32 v138, v138
	v_mul_f32_e32 v142, 0xbfb8aa3b, v142
	v_exp_f32_e32 v142, v142
	v_rcp_f32_e32 v150, v145
	v_add_f32_e32 v138, 1.0, v138
	v_min_f32_e32 v149, 0x7149f2ca, v138
	v_add_f32_e32 v138, 1.0, v142
	v_lshlrev_b32_e32 v142, 16, v139
	v_lshlrev_b32_e32 v145, 16, v143
	v_and_b32_e32 v143, 0xffff0000, v143
	v_mul_f32_e32 v142, 0xbfb8aa3b, v142
	v_mul_f32_e32 v145, 0xbfb8aa3b, v145
	v_mul_f32_e32 v143, 0xbfb8aa3b, v143
	v_exp_f32_e32 v142, v142
	v_exp_f32_e32 v145, v145
	v_exp_f32_e32 v143, v143
	v_and_b32_e32 v139, 0xffff0000, v139
	v_mul_f32_e32 v139, 0xbfb8aa3b, v139
	v_exp_f32_e32 v139, v139
	v_rcp_f32_e32 v151, v138
	v_add_f32_e32 v138, 1.0, v142
	v_add_f32_e32 v142, 1.0, v145
	v_add_f32_e32 v143, 1.0, v143
	v_rcp_f32_e32 v142, v142
	v_rcp_f32_e32 v143, v143
	v_add_f32_e32 v139, 1.0, v139
	v_min_f32_e32 v138, 0x7149f2ca, v138
	v_min_f32_e32 v139, 0x7149f2ca, v139
	v_pk_mul_f32 v[138:139], v[138:139], v[142:143]
	v_lshlrev_b32_e32 v143, 16, v141
	v_pk_mul_f32 v[18:19], v[18:19], v[138:139]
	v_lshlrev_b32_e32 v138, 16, v136
	v_lshlrev_b32_e32 v139, 16, v140
	v_and_b32_e32 v136, 0xffff0000, v136
	v_mul_f32_e32 v139, 0xbfb8aa3b, v139
	v_mul_f32_e32 v136, 0xbfb8aa3b, v136
	v_and_b32_e32 v140, 0xffff0000, v140
	v_exp_f32_e32 v139, v139
	v_exp_f32_e32 v136, v136
	v_mul_f32_e32 v140, 0xbfb8aa3b, v140
	v_exp_f32_e32 v140, v140
	v_add_f32_e32 v139, 1.0, v139
	v_add_f32_e32 v136, 1.0, v136
	v_rcp_f32_e32 v142, v139
	v_min_f32_e32 v139, 0x7149f2ca, v136
	v_add_f32_e32 v136, 1.0, v140
	v_lshlrev_b32_e32 v140, 16, v137
	v_and_b32_e32 v141, 0xffff0000, v141
	v_mul_f32_e32 v140, 0xbfb8aa3b, v140
	v_mul_f32_e32 v143, 0xbfb8aa3b, v143
	v_mul_f32_e32 v141, 0xbfb8aa3b, v141
	v_exp_f32_e32 v140, v140
	v_exp_f32_e32 v145, v143
	v_exp_f32_e32 v141, v141
	v_and_b32_e32 v137, 0xffff0000, v137
	v_mul_f32_e32 v137, 0xbfb8aa3b, v137
	v_exp_f32_e32 v137, v137
	v_rcp_f32_e32 v143, v136
	v_add_f32_e32 v136, 1.0, v140
	v_add_f32_e32 v140, 1.0, v145
	v_add_f32_e32 v141, 1.0, v141
	v_rcp_f32_e32 v140, v140
	v_rcp_f32_e32 v141, v141
	v_add_f32_e32 v137, 1.0, v137
	v_min_f32_e32 v136, 0x7149f2ca, v136
	v_min_f32_e32 v137, 0x7149f2ca, v137
	v_pk_mul_f32 v[136:137], v[136:137], v[140:141]
	v_mul_f32_e32 v138, 0xbfb8aa3b, v138
	v_pk_mul_f32 v[22:23], v[22:23], v[136:137]
	v_pk_mul_f32 v[148:149], v[148:149], v[150:151]
	v_exp_f32_e32 v138, v138
	v_pk_mul_f32 v[16:17], v[16:17], v[148:149]
	v_add_f32_e32 v138, 1.0, v138
	s_waitcnt vmcnt(1)
	v_lshlrev_b32_e32 v136, 16, v130
	v_mul_f32_e32 v136, 0xbfb8aa3b, v136
	v_exp_f32_e32 v136, v136
	s_waitcnt vmcnt(0)
	v_lshlrev_b32_e32 v137, 16, v134
	v_mul_f32_e32 v137, 0xbfb8aa3b, v137
	v_exp_f32_e32 v137, v137
	v_add_f32_e32 v136, 1.0, v136
	v_min_f32_e32 v148, 0x7149f2ca, v136
	v_add_u32_e32 v136, 0x90, v144
	v_add_f32_e32 v145, 1.0, v137
	v_mov_b32_e32 v137, v147
	v_lshlrev_b64 v[136:137], 10, v[136:137]
	v_lshl_add_u64 v[136:137], v[136:137], 0, v[146:147]
	v_lshlrev_b64 v[150:151], 1, v[136:137]
	v_min_f32_e32 v138, 0x7149f2ca, v138
	v_or_b32_e32 v140, 0x100, v150
	v_mov_b32_e32 v141, v151
	v_pk_mul_f32 v[138:139], v[138:139], v[142:143]
	v_lshl_add_u64 v[136:137], s[6:7], 0, v[140:141]
	v_pk_mul_f32 v[20:21], v[20:21], v[138:139]
	global_load_dwordx4 v[136:139], v[136:137], off
	v_lshl_add_u64 v[140:141], s[70:71], 0, v[140:141]
	global_load_dwordx4 v[140:143], v[140:141], off nt
	v_and_b32_e32 v130, 0xffff0000, v130
	v_mul_f32_e32 v130, 0xbfb8aa3b, v130
	v_and_b32_e32 v134, 0xffff0000, v134
	v_exp_f32_e32 v130, v130
	v_mul_f32_e32 v134, 0xbfb8aa3b, v134
	v_exp_f32_e32 v134, v134
	v_rcp_f32_e32 v152, v145
	v_add_f32_e32 v130, 1.0, v130
	v_min_f32_e32 v149, 0x7149f2ca, v130
	v_add_f32_e32 v130, 1.0, v134
	v_lshlrev_b32_e32 v134, 16, v131
	v_lshlrev_b32_e32 v145, 16, v135
	v_and_b32_e32 v135, 0xffff0000, v135
	v_mul_f32_e32 v134, 0xbfb8aa3b, v134
	v_mul_f32_e32 v145, 0xbfb8aa3b, v145
	v_mul_f32_e32 v135, 0xbfb8aa3b, v135
	v_exp_f32_e32 v134, v134
	v_exp_f32_e32 v145, v145
	v_exp_f32_e32 v135, v135
	v_and_b32_e32 v131, 0xffff0000, v131
	v_mul_f32_e32 v131, 0xbfb8aa3b, v131
	v_exp_f32_e32 v131, v131
	v_rcp_f32_e32 v153, v130
	v_add_f32_e32 v130, 1.0, v134
	v_add_f32_e32 v134, 1.0, v145
	v_add_f32_e32 v135, 1.0, v135
	v_rcp_f32_e32 v134, v134
	v_rcp_f32_e32 v135, v135
	v_add_f32_e32 v131, 1.0, v131
	v_min_f32_e32 v130, 0x7149f2ca, v130
	v_min_f32_e32 v131, 0x7149f2ca, v131
	v_pk_mul_f32 v[130:131], v[130:131], v[134:135]
	v_lshlrev_b32_e32 v135, 16, v133
	v_pk_mul_f32 v[26:27], v[26:27], v[130:131]
	v_lshlrev_b32_e32 v130, 16, v128
	v_lshlrev_b32_e32 v131, 16, v132
	v_and_b32_e32 v128, 0xffff0000, v128
	v_mul_f32_e32 v131, 0xbfb8aa3b, v131
	v_mul_f32_e32 v128, 0xbfb8aa3b, v128
	v_and_b32_e32 v132, 0xffff0000, v132
	v_exp_f32_e32 v131, v131
	v_exp_f32_e32 v128, v128
	v_mul_f32_e32 v132, 0xbfb8aa3b, v132
	v_exp_f32_e32 v132, v132
	v_add_f32_e32 v131, 1.0, v131
	v_add_f32_e32 v128, 1.0, v128
	v_rcp_f32_e32 v134, v131
	v_min_f32_e32 v131, 0x7149f2ca, v128
	v_add_f32_e32 v128, 1.0, v132
	v_lshlrev_b32_e32 v132, 16, v129
	v_and_b32_e32 v133, 0xffff0000, v133
	v_mul_f32_e32 v132, 0xbfb8aa3b, v132
	v_mul_f32_e32 v135, 0xbfb8aa3b, v135
	v_mul_f32_e32 v133, 0xbfb8aa3b, v133
	v_exp_f32_e32 v132, v132
	v_exp_f32_e32 v145, v135
	v_exp_f32_e32 v133, v133
	v_and_b32_e32 v129, 0xffff0000, v129
	v_mul_f32_e32 v129, 0xbfb8aa3b, v129
	v_exp_f32_e32 v129, v129
	v_rcp_f32_e32 v135, v128
	v_add_f32_e32 v128, 1.0, v132
	v_add_f32_e32 v132, 1.0, v145
	v_add_f32_e32 v133, 1.0, v133
	v_rcp_f32_e32 v132, v132
	v_rcp_f32_e32 v133, v133
	v_add_f32_e32 v129, 1.0, v129
	v_min_f32_e32 v128, 0x7149f2ca, v128
	v_min_f32_e32 v129, 0x7149f2ca, v129
	v_pk_mul_f32 v[128:129], v[128:129], v[132:133]
	v_mul_f32_e32 v130, 0xbfb8aa3b, v130
	v_pk_mul_f32 v[30:31], v[30:31], v[128:129]
	v_exp_f32_e32 v130, v130
	v_pk_mul_f32 v[148:149], v[148:149], v[152:153]
	v_add_f32_e32 v130, 1.0, v130
	s_waitcnt vmcnt(1)
	v_lshlrev_b32_e32 v128, 16, v138
	v_mul_f32_e32 v128, 0xbfb8aa3b, v128
	s_waitcnt vmcnt(0)
	v_lshlrev_b32_e32 v129, 16, v142
	v_exp_f32_e32 v128, v128
	v_mul_f32_e32 v129, 0xbfb8aa3b, v129
	v_exp_f32_e32 v129, v129
	v_min_f32_e32 v130, 0x7149f2ca, v130
	v_add_f32_e32 v128, 1.0, v128
	v_pk_mul_f32 v[24:25], v[24:25], v[148:149]
	v_pk_mul_f32 v[130:131], v[130:131], v[134:135]
	v_min_f32_e32 v148, 0x7149f2ca, v128
	v_add_f32_e32 v145, 1.0, v129
	v_and_b32_e32 v132, 0xffff0000, v138
	v_lshl_add_u64 v[128:129], s[6:7], 0, v[150:151]
	v_pk_mul_f32 v[28:29], v[28:29], v[130:131]
	global_load_dwordx4 v[128:131], v[128:129], off
	v_mul_f32_e32 v138, 0xbfb8aa3b, v132
	v_lshl_add_u64 v[132:133], s[70:71], 0, v[150:151]
	global_load_dwordx4 v[132:135], v[132:133], off nt
	v_and_b32_e32 v142, 0xffff0000, v142
	v_exp_f32_e32 v138, v138
	v_mul_f32_e32 v142, 0xbfb8aa3b, v142
	v_exp_f32_e32 v142, v142
	v_rcp_f32_e32 v150, v145
	v_add_f32_e32 v138, 1.0, v138
	v_min_f32_e32 v149, 0x7149f2ca, v138
	v_add_f32_e32 v138, 1.0, v142
	v_lshlrev_b32_e32 v142, 16, v139
	v_lshlrev_b32_e32 v145, 16, v143
	v_and_b32_e32 v143, 0xffff0000, v143
	v_mul_f32_e32 v142, 0xbfb8aa3b, v142
	v_mul_f32_e32 v145, 0xbfb8aa3b, v145
	v_mul_f32_e32 v143, 0xbfb8aa3b, v143
	v_exp_f32_e32 v142, v142
	v_exp_f32_e32 v145, v145
	v_exp_f32_e32 v143, v143
	v_and_b32_e32 v139, 0xffff0000, v139
	v_mul_f32_e32 v139, 0xbfb8aa3b, v139
	v_exp_f32_e32 v139, v139
	v_rcp_f32_e32 v151, v138
	v_add_f32_e32 v138, 1.0, v142
	v_add_f32_e32 v142, 1.0, v145
	v_add_f32_e32 v143, 1.0, v143
	v_rcp_f32_e32 v142, v142
	v_rcp_f32_e32 v143, v143
	v_add_f32_e32 v139, 1.0, v139
	v_min_f32_e32 v138, 0x7149f2ca, v138
	v_min_f32_e32 v139, 0x7149f2ca, v139
	v_pk_mul_f32 v[138:139], v[138:139], v[142:143]
	v_lshlrev_b32_e32 v143, 16, v141
	v_pk_mul_f32 v[34:35], v[34:35], v[138:139]
	v_lshlrev_b32_e32 v138, 16, v136
	v_lshlrev_b32_e32 v139, 16, v140
	v_and_b32_e32 v136, 0xffff0000, v136
	v_mul_f32_e32 v139, 0xbfb8aa3b, v139
	v_mul_f32_e32 v136, 0xbfb8aa3b, v136
	v_and_b32_e32 v140, 0xffff0000, v140
	v_exp_f32_e32 v139, v139
	v_exp_f32_e32 v136, v136
	v_mul_f32_e32 v140, 0xbfb8aa3b, v140
	v_exp_f32_e32 v140, v140
	v_add_f32_e32 v139, 1.0, v139
	v_add_f32_e32 v136, 1.0, v136
	v_rcp_f32_e32 v142, v139
	v_min_f32_e32 v139, 0x7149f2ca, v136
	v_add_f32_e32 v136, 1.0, v140
	v_lshlrev_b32_e32 v140, 16, v137
	v_and_b32_e32 v141, 0xffff0000, v141
	v_mul_f32_e32 v140, 0xbfb8aa3b, v140
	v_mul_f32_e32 v143, 0xbfb8aa3b, v143
	v_mul_f32_e32 v141, 0xbfb8aa3b, v141
	v_exp_f32_e32 v140, v140
	v_exp_f32_e32 v145, v143
	v_exp_f32_e32 v141, v141
	v_and_b32_e32 v137, 0xffff0000, v137
	v_mul_f32_e32 v137, 0xbfb8aa3b, v137
	v_exp_f32_e32 v137, v137
	v_rcp_f32_e32 v143, v136
	v_add_f32_e32 v136, 1.0, v140
	v_add_f32_e32 v140, 1.0, v145
	v_add_f32_e32 v141, 1.0, v141
	v_rcp_f32_e32 v140, v140
	v_rcp_f32_e32 v141, v141
	v_add_f32_e32 v137, 1.0, v137
	v_min_f32_e32 v136, 0x7149f2ca, v136
	v_min_f32_e32 v137, 0x7149f2ca, v137
	v_pk_mul_f32 v[136:137], v[136:137], v[140:141]
	v_mul_f32_e32 v138, 0xbfb8aa3b, v138
	v_pk_mul_f32 v[38:39], v[38:39], v[136:137]
	v_pk_mul_f32 v[148:149], v[148:149], v[150:151]
	v_exp_f32_e32 v138, v138
	v_pk_mul_f32 v[32:33], v[32:33], v[148:149]
	v_add_f32_e32 v138, 1.0, v138
	s_waitcnt vmcnt(1)
	v_lshlrev_b32_e32 v136, 16, v130
	v_mul_f32_e32 v136, 0xbfb8aa3b, v136
	v_exp_f32_e32 v136, v136
	s_waitcnt vmcnt(0)
	v_lshlrev_b32_e32 v137, 16, v134
	v_mul_f32_e32 v137, 0xbfb8aa3b, v137
	v_exp_f32_e32 v137, v137
	v_add_f32_e32 v136, 1.0, v136
	v_min_f32_e32 v148, 0x7149f2ca, v136
	v_add_u32_e32 v136, 0x80, v144
	v_add_f32_e32 v145, 1.0, v137
	v_mov_b32_e32 v137, v147
	v_lshlrev_b64 v[136:137], 10, v[136:137]
	v_lshl_add_u64 v[136:137], v[136:137], 0, v[146:147]
	v_lshlrev_b64 v[150:151], 1, v[136:137]
	v_min_f32_e32 v138, 0x7149f2ca, v138
	v_or_b32_e32 v140, 0x100, v150
	v_mov_b32_e32 v141, v151
	v_pk_mul_f32 v[138:139], v[138:139], v[142:143]
	v_lshl_add_u64 v[136:137], s[6:7], 0, v[140:141]
	v_pk_mul_f32 v[36:37], v[36:37], v[138:139]
	global_load_dwordx4 v[136:139], v[136:137], off
	v_lshl_add_u64 v[140:141], s[70:71], 0, v[140:141]
	global_load_dwordx4 v[140:143], v[140:141], off nt
	v_and_b32_e32 v130, 0xffff0000, v130
	v_mul_f32_e32 v130, 0xbfb8aa3b, v130
	v_and_b32_e32 v134, 0xffff0000, v134
	v_exp_f32_e32 v130, v130
	v_mul_f32_e32 v134, 0xbfb8aa3b, v134
	v_exp_f32_e32 v134, v134
	v_rcp_f32_e32 v152, v145
	v_add_f32_e32 v130, 1.0, v130
	v_min_f32_e32 v149, 0x7149f2ca, v130
	v_add_f32_e32 v130, 1.0, v134
	v_lshlrev_b32_e32 v134, 16, v131
	v_lshlrev_b32_e32 v145, 16, v135
	v_and_b32_e32 v135, 0xffff0000, v135
	v_mul_f32_e32 v134, 0xbfb8aa3b, v134
	v_mul_f32_e32 v145, 0xbfb8aa3b, v145
	v_mul_f32_e32 v135, 0xbfb8aa3b, v135
	v_exp_f32_e32 v134, v134
	v_exp_f32_e32 v145, v145
	v_exp_f32_e32 v135, v135
	v_and_b32_e32 v131, 0xffff0000, v131
	v_mul_f32_e32 v131, 0xbfb8aa3b, v131
	v_exp_f32_e32 v131, v131
	v_rcp_f32_e32 v153, v130
	v_add_f32_e32 v130, 1.0, v134
	v_add_f32_e32 v134, 1.0, v145
	v_add_f32_e32 v135, 1.0, v135
	v_rcp_f32_e32 v134, v134
	v_rcp_f32_e32 v135, v135
	v_add_f32_e32 v131, 1.0, v131
	v_min_f32_e32 v130, 0x7149f2ca, v130
	v_min_f32_e32 v131, 0x7149f2ca, v131
	v_pk_mul_f32 v[130:131], v[130:131], v[134:135]
	v_lshlrev_b32_e32 v135, 16, v133
	v_pk_mul_f32 v[54:55], v[54:55], v[130:131]
	v_lshlrev_b32_e32 v130, 16, v128
	v_lshlrev_b32_e32 v131, 16, v132
	v_and_b32_e32 v128, 0xffff0000, v128
	v_mul_f32_e32 v131, 0xbfb8aa3b, v131
	v_mul_f32_e32 v128, 0xbfb8aa3b, v128
	v_and_b32_e32 v132, 0xffff0000, v132
	v_exp_f32_e32 v131, v131
	v_exp_f32_e32 v128, v128
	v_mul_f32_e32 v132, 0xbfb8aa3b, v132
	v_exp_f32_e32 v132, v132
	v_add_f32_e32 v131, 1.0, v131
	v_add_f32_e32 v128, 1.0, v128
	v_rcp_f32_e32 v134, v131
	v_min_f32_e32 v131, 0x7149f2ca, v128
	v_add_f32_e32 v128, 1.0, v132
	v_lshlrev_b32_e32 v132, 16, v129
	v_and_b32_e32 v133, 0xffff0000, v133
	v_mul_f32_e32 v132, 0xbfb8aa3b, v132
	v_mul_f32_e32 v135, 0xbfb8aa3b, v135
	v_mul_f32_e32 v133, 0xbfb8aa3b, v133
	v_exp_f32_e32 v132, v132
	v_exp_f32_e32 v145, v135
	v_exp_f32_e32 v133, v133
	v_and_b32_e32 v129, 0xffff0000, v129
	v_mul_f32_e32 v129, 0xbfb8aa3b, v129
	v_exp_f32_e32 v129, v129
	v_rcp_f32_e32 v135, v128
	v_add_f32_e32 v128, 1.0, v132
	v_add_f32_e32 v132, 1.0, v145
	v_add_f32_e32 v133, 1.0, v133
	v_rcp_f32_e32 v132, v132
	v_rcp_f32_e32 v133, v133
	v_add_f32_e32 v129, 1.0, v129
	v_min_f32_e32 v128, 0x7149f2ca, v128
	v_min_f32_e32 v129, 0x7149f2ca, v129
	v_pk_mul_f32 v[128:129], v[128:129], v[132:133]
	v_mul_f32_e32 v130, 0xbfb8aa3b, v130
	v_pk_mul_f32 v[62:63], v[62:63], v[128:129]
	v_exp_f32_e32 v130, v130
	v_pk_mul_f32 v[148:149], v[148:149], v[152:153]
	v_add_f32_e32 v130, 1.0, v130
	s_waitcnt vmcnt(1)
	v_lshlrev_b32_e32 v128, 16, v138
	v_mul_f32_e32 v128, 0xbfb8aa3b, v128
	s_waitcnt vmcnt(0)
	v_lshlrev_b32_e32 v129, 16, v142
	v_exp_f32_e32 v128, v128
	v_mul_f32_e32 v129, 0xbfb8aa3b, v129
	v_exp_f32_e32 v129, v129
	v_min_f32_e32 v130, 0x7149f2ca, v130
	v_add_f32_e32 v128, 1.0, v128
	v_pk_mul_f32 v[52:53], v[52:53], v[148:149]
	v_pk_mul_f32 v[130:131], v[130:131], v[134:135]
	v_min_f32_e32 v148, 0x7149f2ca, v128
	v_add_f32_e32 v145, 1.0, v129
	v_and_b32_e32 v132, 0xffff0000, v138
	v_lshl_add_u64 v[128:129], s[6:7], 0, v[150:151]
	v_pk_mul_f32 v[60:61], v[60:61], v[130:131]
	global_load_dwordx4 v[128:131], v[128:129], off
	v_mul_f32_e32 v138, 0xbfb8aa3b, v132
	v_lshl_add_u64 v[132:133], s[70:71], 0, v[150:151]
	global_load_dwordx4 v[132:135], v[132:133], off nt
	v_and_b32_e32 v142, 0xffff0000, v142
	v_exp_f32_e32 v138, v138
	v_mul_f32_e32 v142, 0xbfb8aa3b, v142
	v_exp_f32_e32 v142, v142
	v_rcp_f32_e32 v150, v145
	v_add_f32_e32 v138, 1.0, v138
	v_min_f32_e32 v149, 0x7149f2ca, v138
	v_add_f32_e32 v138, 1.0, v142
	v_lshlrev_b32_e32 v142, 16, v139
	v_lshlrev_b32_e32 v145, 16, v143
	v_and_b32_e32 v143, 0xffff0000, v143
	v_mul_f32_e32 v142, 0xbfb8aa3b, v142
	v_mul_f32_e32 v145, 0xbfb8aa3b, v145
	v_mul_f32_e32 v143, 0xbfb8aa3b, v143
	v_exp_f32_e32 v142, v142
	v_exp_f32_e32 v145, v145
	v_exp_f32_e32 v143, v143
	v_and_b32_e32 v139, 0xffff0000, v139
	v_mul_f32_e32 v139, 0xbfb8aa3b, v139
	v_exp_f32_e32 v139, v139
	v_rcp_f32_e32 v151, v138
	v_add_f32_e32 v138, 1.0, v142
	v_add_f32_e32 v142, 1.0, v145
	v_add_f32_e32 v143, 1.0, v143
	v_rcp_f32_e32 v142, v142
	v_rcp_f32_e32 v143, v143
	v_add_f32_e32 v139, 1.0, v139
	v_min_f32_e32 v138, 0x7149f2ca, v138
	v_min_f32_e32 v139, 0x7149f2ca, v139
	v_pk_mul_f32 v[138:139], v[138:139], v[142:143]
	v_lshlrev_b32_e32 v143, 16, v141
	v_pk_mul_f32 v[74:75], v[74:75], v[138:139]
	v_lshlrev_b32_e32 v138, 16, v136
	v_lshlrev_b32_e32 v139, 16, v140
	v_and_b32_e32 v136, 0xffff0000, v136
	v_mul_f32_e32 v139, 0xbfb8aa3b, v139
	v_mul_f32_e32 v136, 0xbfb8aa3b, v136
	v_and_b32_e32 v140, 0xffff0000, v140
	v_exp_f32_e32 v139, v139
	v_exp_f32_e32 v136, v136
	v_mul_f32_e32 v140, 0xbfb8aa3b, v140
	v_exp_f32_e32 v140, v140
	v_add_f32_e32 v139, 1.0, v139
	v_add_f32_e32 v136, 1.0, v136
	v_rcp_f32_e32 v142, v139
	v_min_f32_e32 v139, 0x7149f2ca, v136
	v_add_f32_e32 v136, 1.0, v140
	v_lshlrev_b32_e32 v140, 16, v137
	v_and_b32_e32 v141, 0xffff0000, v141
	v_mul_f32_e32 v140, 0xbfb8aa3b, v140
	v_mul_f32_e32 v143, 0xbfb8aa3b, v143
	v_mul_f32_e32 v141, 0xbfb8aa3b, v141
	v_exp_f32_e32 v140, v140
	v_exp_f32_e32 v145, v143
	v_exp_f32_e32 v141, v141
	v_and_b32_e32 v137, 0xffff0000, v137
	v_mul_f32_e32 v137, 0xbfb8aa3b, v137
	v_exp_f32_e32 v137, v137
	v_rcp_f32_e32 v143, v136
	v_add_f32_e32 v136, 1.0, v140
	v_add_f32_e32 v140, 1.0, v145
	v_add_f32_e32 v141, 1.0, v141
	v_rcp_f32_e32 v140, v140
	v_rcp_f32_e32 v141, v141
	v_add_f32_e32 v137, 1.0, v137
	v_min_f32_e32 v136, 0x7149f2ca, v136
	v_min_f32_e32 v137, 0x7149f2ca, v137
	v_pk_mul_f32 v[136:137], v[136:137], v[140:141]
	v_mul_f32_e32 v138, 0xbfb8aa3b, v138
	v_pk_mul_f32 v[78:79], v[78:79], v[136:137]
	v_pk_mul_f32 v[148:149], v[148:149], v[150:151]
	v_exp_f32_e32 v138, v138
	v_pk_mul_f32 v[72:73], v[72:73], v[148:149]
	v_add_f32_e32 v138, 1.0, v138
	s_waitcnt vmcnt(1)
	v_lshlrev_b32_e32 v136, 16, v130
	v_mul_f32_e32 v136, 0xbfb8aa3b, v136
	v_exp_f32_e32 v136, v136
	s_waitcnt vmcnt(0)
	v_lshlrev_b32_e32 v137, 16, v134
	v_mul_f32_e32 v137, 0xbfb8aa3b, v137
	v_exp_f32_e32 v137, v137
	v_add_f32_e32 v136, 1.0, v136
	v_min_f32_e32 v148, 0x7149f2ca, v136
	v_or_b32_e32 v136, 48, v144
	v_add_f32_e32 v145, 1.0, v137
	v_mov_b32_e32 v137, v147
	v_lshlrev_b64 v[136:137], 10, v[136:137]
	v_lshl_add_u64 v[136:137], v[136:137], 0, v[146:147]
	v_lshlrev_b64 v[150:151], 1, v[136:137]
	v_min_f32_e32 v138, 0x7149f2ca, v138
	v_or_b32_e32 v140, 0x100, v150
	v_mov_b32_e32 v141, v151
	v_pk_mul_f32 v[138:139], v[138:139], v[142:143]
	v_lshl_add_u64 v[136:137], s[6:7], 0, v[140:141]
	v_pk_mul_f32 v[76:77], v[76:77], v[138:139]
	global_load_dwordx4 v[136:139], v[136:137], off
	v_lshl_add_u64 v[140:141], s[70:71], 0, v[140:141]
	global_load_dwordx4 v[140:143], v[140:141], off nt
	v_and_b32_e32 v130, 0xffff0000, v130
	v_mul_f32_e32 v130, 0xbfb8aa3b, v130
	v_and_b32_e32 v134, 0xffff0000, v134
	v_exp_f32_e32 v130, v130
	v_mul_f32_e32 v134, 0xbfb8aa3b, v134
	v_exp_f32_e32 v134, v134
	v_rcp_f32_e32 v152, v145
	v_add_f32_e32 v130, 1.0, v130
	v_min_f32_e32 v149, 0x7149f2ca, v130
	v_add_f32_e32 v130, 1.0, v134
	v_lshlrev_b32_e32 v134, 16, v131
	v_lshlrev_b32_e32 v145, 16, v135
	v_and_b32_e32 v135, 0xffff0000, v135
	v_mul_f32_e32 v134, 0xbfb8aa3b, v134
	v_mul_f32_e32 v145, 0xbfb8aa3b, v145
	v_mul_f32_e32 v135, 0xbfb8aa3b, v135
	v_exp_f32_e32 v134, v134
	v_exp_f32_e32 v145, v145
	v_exp_f32_e32 v135, v135
	v_and_b32_e32 v131, 0xffff0000, v131
	v_mul_f32_e32 v131, 0xbfb8aa3b, v131
	v_exp_f32_e32 v131, v131
	v_rcp_f32_e32 v153, v130
	v_add_f32_e32 v130, 1.0, v134
	v_add_f32_e32 v134, 1.0, v145
	v_add_f32_e32 v135, 1.0, v135
	v_rcp_f32_e32 v134, v134
	v_rcp_f32_e32 v135, v135
	v_add_f32_e32 v131, 1.0, v131
	v_min_f32_e32 v130, 0x7149f2ca, v130
	v_min_f32_e32 v131, 0x7149f2ca, v131
	v_pk_mul_f32 v[130:131], v[130:131], v[134:135]
	v_lshlrev_b32_e32 v135, 16, v133
	v_pk_mul_f32 v[94:95], v[94:95], v[130:131]
	v_lshlrev_b32_e32 v130, 16, v128
	v_lshlrev_b32_e32 v131, 16, v132
	v_and_b32_e32 v128, 0xffff0000, v128
	v_mul_f32_e32 v131, 0xbfb8aa3b, v131
	v_mul_f32_e32 v128, 0xbfb8aa3b, v128
	v_and_b32_e32 v132, 0xffff0000, v132
	v_exp_f32_e32 v131, v131
	v_exp_f32_e32 v128, v128
	v_mul_f32_e32 v132, 0xbfb8aa3b, v132
	v_exp_f32_e32 v132, v132
	v_add_f32_e32 v131, 1.0, v131
	v_add_f32_e32 v128, 1.0, v128
	v_rcp_f32_e32 v134, v131
	v_min_f32_e32 v131, 0x7149f2ca, v128
	v_add_f32_e32 v128, 1.0, v132
	v_lshlrev_b32_e32 v132, 16, v129
	v_and_b32_e32 v133, 0xffff0000, v133
	v_mul_f32_e32 v132, 0xbfb8aa3b, v132
	v_mul_f32_e32 v135, 0xbfb8aa3b, v135
	v_mul_f32_e32 v133, 0xbfb8aa3b, v133
	v_exp_f32_e32 v132, v132
	v_exp_f32_e32 v145, v135
	v_exp_f32_e32 v133, v133
	v_and_b32_e32 v129, 0xffff0000, v129
	v_mul_f32_e32 v129, 0xbfb8aa3b, v129
	v_exp_f32_e32 v129, v129
	v_rcp_f32_e32 v135, v128
	v_add_f32_e32 v128, 1.0, v132
	v_add_f32_e32 v132, 1.0, v145
	v_add_f32_e32 v133, 1.0, v133
	v_rcp_f32_e32 v132, v132
	v_rcp_f32_e32 v133, v133
	v_add_f32_e32 v129, 1.0, v129
	v_min_f32_e32 v128, 0x7149f2ca, v128
	v_min_f32_e32 v129, 0x7149f2ca, v129
	v_pk_mul_f32 v[128:129], v[128:129], v[132:133]
	v_mul_f32_e32 v130, 0xbfb8aa3b, v130
	v_pk_mul_f32 v[102:103], v[102:103], v[128:129]
	v_exp_f32_e32 v130, v130
	v_pk_mul_f32 v[148:149], v[148:149], v[152:153]
	v_add_f32_e32 v130, 1.0, v130
	s_waitcnt vmcnt(1)
	v_lshlrev_b32_e32 v128, 16, v138
	v_mul_f32_e32 v128, 0xbfb8aa3b, v128
	s_waitcnt vmcnt(0)
	v_lshlrev_b32_e32 v129, 16, v142
	v_exp_f32_e32 v128, v128
	v_mul_f32_e32 v129, 0xbfb8aa3b, v129
	v_exp_f32_e32 v129, v129
	v_min_f32_e32 v130, 0x7149f2ca, v130
	v_add_f32_e32 v128, 1.0, v128
	v_pk_mul_f32 v[92:93], v[92:93], v[148:149]
	v_pk_mul_f32 v[130:131], v[130:131], v[134:135]
	v_min_f32_e32 v148, 0x7149f2ca, v128
	v_add_f32_e32 v145, 1.0, v129
	v_and_b32_e32 v132, 0xffff0000, v138
	v_lshl_add_u64 v[128:129], s[6:7], 0, v[150:151]
	v_pk_mul_f32 v[100:101], v[100:101], v[130:131]
	global_load_dwordx4 v[128:131], v[128:129], off
	v_mul_f32_e32 v138, 0xbfb8aa3b, v132
	v_lshl_add_u64 v[132:133], s[70:71], 0, v[150:151]
	global_load_dwordx4 v[132:135], v[132:133], off nt
	v_and_b32_e32 v142, 0xffff0000, v142
	v_exp_f32_e32 v138, v138
	v_mul_f32_e32 v142, 0xbfb8aa3b, v142
	v_exp_f32_e32 v142, v142
	v_rcp_f32_e32 v150, v145
	v_add_f32_e32 v138, 1.0, v138
	v_min_f32_e32 v149, 0x7149f2ca, v138
	v_add_f32_e32 v138, 1.0, v142
	v_lshlrev_b32_e32 v142, 16, v139
	v_lshlrev_b32_e32 v145, 16, v143
	v_and_b32_e32 v143, 0xffff0000, v143
	v_mul_f32_e32 v142, 0xbfb8aa3b, v142
	v_mul_f32_e32 v145, 0xbfb8aa3b, v145
	v_mul_f32_e32 v143, 0xbfb8aa3b, v143
	v_exp_f32_e32 v142, v142
	v_exp_f32_e32 v145, v145
	v_exp_f32_e32 v143, v143
	v_and_b32_e32 v139, 0xffff0000, v139
	v_mul_f32_e32 v139, 0xbfb8aa3b, v139
	v_exp_f32_e32 v139, v139
	v_rcp_f32_e32 v151, v138
	v_add_f32_e32 v138, 1.0, v142
	v_add_f32_e32 v142, 1.0, v145
	v_add_f32_e32 v143, 1.0, v143
	v_rcp_f32_e32 v142, v142
	v_rcp_f32_e32 v143, v143
	v_add_f32_e32 v139, 1.0, v139
	v_min_f32_e32 v138, 0x7149f2ca, v138
	v_min_f32_e32 v139, 0x7149f2ca, v139
	v_pk_mul_f32 v[138:139], v[138:139], v[142:143]
	v_lshlrev_b32_e32 v143, 16, v141
	v_pk_mul_f32 v[114:115], v[114:115], v[138:139]
	v_lshlrev_b32_e32 v138, 16, v136
	v_lshlrev_b32_e32 v139, 16, v140
	v_and_b32_e32 v136, 0xffff0000, v136
	v_mul_f32_e32 v139, 0xbfb8aa3b, v139
	v_mul_f32_e32 v136, 0xbfb8aa3b, v136
	v_and_b32_e32 v140, 0xffff0000, v140
	v_exp_f32_e32 v139, v139
	v_exp_f32_e32 v136, v136
	v_mul_f32_e32 v140, 0xbfb8aa3b, v140
	v_exp_f32_e32 v140, v140
	v_add_f32_e32 v139, 1.0, v139
	v_add_f32_e32 v136, 1.0, v136
	v_rcp_f32_e32 v142, v139
	v_min_f32_e32 v139, 0x7149f2ca, v136
	v_add_f32_e32 v136, 1.0, v140
	v_lshlrev_b32_e32 v140, 16, v137
	v_and_b32_e32 v141, 0xffff0000, v141
	v_mul_f32_e32 v140, 0xbfb8aa3b, v140
	v_mul_f32_e32 v143, 0xbfb8aa3b, v143
	v_mul_f32_e32 v141, 0xbfb8aa3b, v141
	v_exp_f32_e32 v140, v140
	v_exp_f32_e32 v145, v143
	v_exp_f32_e32 v141, v141
	v_and_b32_e32 v137, 0xffff0000, v137
	v_mul_f32_e32 v137, 0xbfb8aa3b, v137
	v_exp_f32_e32 v137, v137
	v_rcp_f32_e32 v143, v136
	v_add_f32_e32 v136, 1.0, v140
	v_add_f32_e32 v140, 1.0, v145
	v_add_f32_e32 v141, 1.0, v141
	v_rcp_f32_e32 v140, v140
	v_rcp_f32_e32 v141, v141
	v_add_f32_e32 v137, 1.0, v137
	v_min_f32_e32 v136, 0x7149f2ca, v136
	v_min_f32_e32 v137, 0x7149f2ca, v137
	v_pk_mul_f32 v[136:137], v[136:137], v[140:141]
	v_mul_f32_e32 v138, 0xbfb8aa3b, v138
	v_pk_mul_f32 v[118:119], v[118:119], v[136:137]
	v_pk_mul_f32 v[148:149], v[148:149], v[150:151]
	v_exp_f32_e32 v138, v138
	v_pk_mul_f32 v[112:113], v[112:113], v[148:149]
	v_add_f32_e32 v138, 1.0, v138
	s_waitcnt vmcnt(1)
	v_lshlrev_b32_e32 v136, 16, v130
	v_mul_f32_e32 v136, 0xbfb8aa3b, v136
	v_exp_f32_e32 v136, v136
	s_waitcnt vmcnt(0)
	v_lshlrev_b32_e32 v137, 16, v134
	v_mul_f32_e32 v137, 0xbfb8aa3b, v137
	v_exp_f32_e32 v137, v137
	v_add_f32_e32 v136, 1.0, v136
	v_min_f32_e32 v148, 0x7149f2ca, v136
	v_or_b32_e32 v136, 32, v144
	v_add_f32_e32 v145, 1.0, v137
	v_mov_b32_e32 v137, v147
	v_lshlrev_b64 v[136:137], 10, v[136:137]
	v_lshl_add_u64 v[136:137], v[136:137], 0, v[146:147]
	v_lshlrev_b64 v[150:151], 1, v[136:137]
	v_min_f32_e32 v138, 0x7149f2ca, v138
	v_or_b32_e32 v140, 0x100, v150
	v_mov_b32_e32 v141, v151
	v_pk_mul_f32 v[138:139], v[138:139], v[142:143]
	v_lshl_add_u64 v[136:137], s[6:7], 0, v[140:141]
	v_pk_mul_f32 v[116:117], v[116:117], v[138:139]
	global_load_dwordx4 v[136:139], v[136:137], off
	v_lshl_add_u64 v[140:141], s[70:71], 0, v[140:141]
	global_load_dwordx4 v[140:143], v[140:141], off nt
	v_and_b32_e32 v130, 0xffff0000, v130
	v_mul_f32_e32 v130, 0xbfb8aa3b, v130
	v_and_b32_e32 v134, 0xffff0000, v134
	v_exp_f32_e32 v130, v130
	v_mul_f32_e32 v134, 0xbfb8aa3b, v134
	v_exp_f32_e32 v134, v134
	v_rcp_f32_e32 v152, v145
	v_add_f32_e32 v130, 1.0, v130
	v_min_f32_e32 v149, 0x7149f2ca, v130
	v_add_f32_e32 v130, 1.0, v134
	v_lshlrev_b32_e32 v134, 16, v131
	v_lshlrev_b32_e32 v145, 16, v135
	v_and_b32_e32 v135, 0xffff0000, v135
	v_mul_f32_e32 v134, 0xbfb8aa3b, v134
	v_mul_f32_e32 v145, 0xbfb8aa3b, v145
	v_mul_f32_e32 v135, 0xbfb8aa3b, v135
	v_exp_f32_e32 v134, v134
	v_exp_f32_e32 v145, v145
	v_exp_f32_e32 v135, v135
	v_and_b32_e32 v131, 0xffff0000, v131
	v_mul_f32_e32 v131, 0xbfb8aa3b, v131
	v_exp_f32_e32 v131, v131
	v_rcp_f32_e32 v153, v130
	v_add_f32_e32 v130, 1.0, v134
	v_add_f32_e32 v134, 1.0, v145
	v_add_f32_e32 v135, 1.0, v135
	v_rcp_f32_e32 v134, v134
	v_rcp_f32_e32 v135, v135
	v_add_f32_e32 v131, 1.0, v131
	v_min_f32_e32 v130, 0x7149f2ca, v130
	v_min_f32_e32 v131, 0x7149f2ca, v131
	v_pk_mul_f32 v[130:131], v[130:131], v[134:135]
	v_lshlrev_b32_e32 v135, 16, v133
	v_pk_mul_f32 v[126:127], v[126:127], v[130:131]
	v_lshlrev_b32_e32 v130, 16, v128
	v_lshlrev_b32_e32 v131, 16, v132
	v_and_b32_e32 v128, 0xffff0000, v128
	v_mul_f32_e32 v131, 0xbfb8aa3b, v131
	v_mul_f32_e32 v128, 0xbfb8aa3b, v128
	v_and_b32_e32 v132, 0xffff0000, v132
	v_exp_f32_e32 v131, v131
	v_exp_f32_e32 v128, v128
	v_mul_f32_e32 v132, 0xbfb8aa3b, v132
	v_exp_f32_e32 v132, v132
	v_add_f32_e32 v131, 1.0, v131
	v_add_f32_e32 v128, 1.0, v128
	v_rcp_f32_e32 v134, v131
	v_min_f32_e32 v131, 0x7149f2ca, v128
	v_add_f32_e32 v128, 1.0, v132
	v_lshlrev_b32_e32 v132, 16, v129
	v_and_b32_e32 v133, 0xffff0000, v133
	v_mul_f32_e32 v132, 0xbfb8aa3b, v132
	v_mul_f32_e32 v135, 0xbfb8aa3b, v135
	v_mul_f32_e32 v133, 0xbfb8aa3b, v133
	v_exp_f32_e32 v132, v132
	v_exp_f32_e32 v145, v135
	v_exp_f32_e32 v133, v133
	v_and_b32_e32 v129, 0xffff0000, v129
	v_mul_f32_e32 v129, 0xbfb8aa3b, v129
	v_exp_f32_e32 v129, v129
	v_rcp_f32_e32 v135, v128
	v_add_f32_e32 v128, 1.0, v132
	v_add_f32_e32 v132, 1.0, v145
	v_add_f32_e32 v133, 1.0, v133
	v_rcp_f32_e32 v132, v132
	v_rcp_f32_e32 v133, v133
	v_add_f32_e32 v129, 1.0, v129
	v_min_f32_e32 v128, 0x7149f2ca, v128
	v_min_f32_e32 v129, 0x7149f2ca, v129
	v_pk_mul_f32 v[128:129], v[128:129], v[132:133]
	v_mul_f32_e32 v130, 0xbfb8aa3b, v130
	v_pk_mul_f32 v[122:123], v[122:123], v[128:129]
	v_exp_f32_e32 v130, v130
	v_pk_mul_f32 v[148:149], v[148:149], v[152:153]
	v_add_f32_e32 v130, 1.0, v130
	s_waitcnt vmcnt(1)
	v_lshlrev_b32_e32 v128, 16, v138
	v_mul_f32_e32 v128, 0xbfb8aa3b, v128
	s_waitcnt vmcnt(0)
	v_lshlrev_b32_e32 v129, 16, v142
	v_exp_f32_e32 v128, v128
	v_mul_f32_e32 v129, 0xbfb8aa3b, v129
	v_exp_f32_e32 v129, v129
	v_min_f32_e32 v130, 0x7149f2ca, v130
	v_add_f32_e32 v128, 1.0, v128
	v_pk_mul_f32 v[124:125], v[124:125], v[148:149]
	v_pk_mul_f32 v[130:131], v[130:131], v[134:135]
	v_min_f32_e32 v148, 0x7149f2ca, v128
	v_add_f32_e32 v145, 1.0, v129
	v_and_b32_e32 v132, 0xffff0000, v138
	v_lshl_add_u64 v[128:129], s[6:7], 0, v[150:151]
	v_pk_mul_f32 v[120:121], v[120:121], v[130:131]
	global_load_dwordx4 v[128:131], v[128:129], off
	v_mul_f32_e32 v138, 0xbfb8aa3b, v132
	v_lshl_add_u64 v[132:133], s[70:71], 0, v[150:151]
	global_load_dwordx4 v[132:135], v[132:133], off nt
	v_and_b32_e32 v142, 0xffff0000, v142
	v_exp_f32_e32 v138, v138
	v_mul_f32_e32 v142, 0xbfb8aa3b, v142
	v_exp_f32_e32 v142, v142
	v_rcp_f32_e32 v150, v145
	v_add_f32_e32 v138, 1.0, v138
	v_min_f32_e32 v149, 0x7149f2ca, v138
	v_add_f32_e32 v138, 1.0, v142
	v_lshlrev_b32_e32 v142, 16, v139
	v_lshlrev_b32_e32 v145, 16, v143
	v_and_b32_e32 v143, 0xffff0000, v143
	v_mul_f32_e32 v142, 0xbfb8aa3b, v142
	v_mul_f32_e32 v145, 0xbfb8aa3b, v145
	v_mul_f32_e32 v143, 0xbfb8aa3b, v143
	v_exp_f32_e32 v142, v142
	v_exp_f32_e32 v145, v145
	v_exp_f32_e32 v143, v143
	v_and_b32_e32 v139, 0xffff0000, v139
	v_mul_f32_e32 v139, 0xbfb8aa3b, v139
	v_exp_f32_e32 v139, v139
	v_rcp_f32_e32 v151, v138
	v_add_f32_e32 v138, 1.0, v142
	v_add_f32_e32 v142, 1.0, v145
	v_add_f32_e32 v143, 1.0, v143
	v_rcp_f32_e32 v142, v142
	v_rcp_f32_e32 v143, v143
	v_add_f32_e32 v139, 1.0, v139
	v_min_f32_e32 v138, 0x7149f2ca, v138
	v_min_f32_e32 v139, 0x7149f2ca, v139
	v_pk_mul_f32 v[138:139], v[138:139], v[142:143]
	v_lshlrev_b32_e32 v143, 16, v141
	v_pk_mul_f32 v[110:111], v[110:111], v[138:139]
	v_lshlrev_b32_e32 v138, 16, v136
	v_lshlrev_b32_e32 v139, 16, v140
	v_and_b32_e32 v136, 0xffff0000, v136
	v_mul_f32_e32 v139, 0xbfb8aa3b, v139
	v_mul_f32_e32 v136, 0xbfb8aa3b, v136
	v_and_b32_e32 v140, 0xffff0000, v140
	v_exp_f32_e32 v139, v139
	v_exp_f32_e32 v136, v136
	v_mul_f32_e32 v140, 0xbfb8aa3b, v140
	v_exp_f32_e32 v140, v140
	v_add_f32_e32 v139, 1.0, v139
	v_add_f32_e32 v136, 1.0, v136
	v_rcp_f32_e32 v142, v139
	v_min_f32_e32 v139, 0x7149f2ca, v136
	v_add_f32_e32 v136, 1.0, v140
	v_lshlrev_b32_e32 v140, 16, v137
	v_and_b32_e32 v141, 0xffff0000, v141
	v_mul_f32_e32 v140, 0xbfb8aa3b, v140
	v_mul_f32_e32 v143, 0xbfb8aa3b, v143
	v_mul_f32_e32 v141, 0xbfb8aa3b, v141
	v_exp_f32_e32 v140, v140
	v_exp_f32_e32 v145, v143
	v_exp_f32_e32 v141, v141
	v_and_b32_e32 v137, 0xffff0000, v137
	v_mul_f32_e32 v137, 0xbfb8aa3b, v137
	v_exp_f32_e32 v137, v137
	v_rcp_f32_e32 v143, v136
	v_add_f32_e32 v136, 1.0, v140
	v_add_f32_e32 v140, 1.0, v145
	v_add_f32_e32 v141, 1.0, v141
	v_rcp_f32_e32 v140, v140
	v_rcp_f32_e32 v141, v141
	v_add_f32_e32 v137, 1.0, v137
	v_min_f32_e32 v136, 0x7149f2ca, v136
	v_min_f32_e32 v137, 0x7149f2ca, v137
	v_pk_mul_f32 v[136:137], v[136:137], v[140:141]
	v_mul_f32_e32 v138, 0xbfb8aa3b, v138
	v_pk_mul_f32 v[106:107], v[106:107], v[136:137]
	v_pk_mul_f32 v[148:149], v[148:149], v[150:151]
	v_exp_f32_e32 v138, v138
	v_pk_mul_f32 v[108:109], v[108:109], v[148:149]
	v_add_f32_e32 v138, 1.0, v138
	s_waitcnt vmcnt(1)
	v_lshlrev_b32_e32 v136, 16, v130
	v_mul_f32_e32 v136, 0xbfb8aa3b, v136
	v_exp_f32_e32 v136, v136
	s_waitcnt vmcnt(0)
	v_lshlrev_b32_e32 v137, 16, v134
	v_mul_f32_e32 v137, 0xbfb8aa3b, v137
	v_exp_f32_e32 v137, v137
	v_add_f32_e32 v136, 1.0, v136
	v_min_f32_e32 v148, 0x7149f2ca, v136
	v_or_b32_e32 v136, 16, v144
	v_add_f32_e32 v145, 1.0, v137
	v_mov_b32_e32 v137, v147
	v_lshlrev_b64 v[136:137], 10, v[136:137]
	v_lshl_add_u64 v[136:137], v[136:137], 0, v[146:147]
	v_lshlrev_b64 v[150:151], 1, v[136:137]
	v_min_f32_e32 v138, 0x7149f2ca, v138
	v_or_b32_e32 v140, 0x100, v150
	v_mov_b32_e32 v141, v151
	v_pk_mul_f32 v[138:139], v[138:139], v[142:143]
	v_lshl_add_u64 v[136:137], s[6:7], 0, v[140:141]
	v_pk_mul_f32 v[104:105], v[104:105], v[138:139]
	global_load_dwordx4 v[136:139], v[136:137], off
	v_lshl_add_u64 v[140:141], s[70:71], 0, v[140:141]
	global_load_dwordx4 v[140:143], v[140:141], off nt
	v_and_b32_e32 v130, 0xffff0000, v130
	v_mul_f32_e32 v130, 0xbfb8aa3b, v130
	v_and_b32_e32 v134, 0xffff0000, v134
	v_exp_f32_e32 v130, v130
	v_mul_f32_e32 v134, 0xbfb8aa3b, v134
	v_exp_f32_e32 v134, v134
	v_rcp_f32_e32 v152, v145
	v_add_f32_e32 v130, 1.0, v130
	v_min_f32_e32 v149, 0x7149f2ca, v130
	v_add_f32_e32 v130, 1.0, v134
	v_lshlrev_b32_e32 v134, 16, v131
	v_lshlrev_b32_e32 v145, 16, v135
	v_and_b32_e32 v135, 0xffff0000, v135
	v_mul_f32_e32 v134, 0xbfb8aa3b, v134
	v_mul_f32_e32 v145, 0xbfb8aa3b, v145
	v_mul_f32_e32 v135, 0xbfb8aa3b, v135
	v_exp_f32_e32 v134, v134
	v_exp_f32_e32 v145, v145
	v_exp_f32_e32 v135, v135
	v_and_b32_e32 v131, 0xffff0000, v131
	v_mul_f32_e32 v131, 0xbfb8aa3b, v131
	v_exp_f32_e32 v131, v131
	v_rcp_f32_e32 v153, v130
	v_add_f32_e32 v130, 1.0, v134
	v_add_f32_e32 v134, 1.0, v145
	v_add_f32_e32 v135, 1.0, v135
	v_rcp_f32_e32 v134, v134
	v_rcp_f32_e32 v135, v135
	v_add_f32_e32 v131, 1.0, v131
	v_min_f32_e32 v130, 0x7149f2ca, v130
	v_min_f32_e32 v131, 0x7149f2ca, v131
	v_pk_mul_f32 v[130:131], v[130:131], v[134:135]
	v_lshlrev_b32_e32 v135, 16, v133
	v_pk_mul_f32 v[98:99], v[98:99], v[130:131]
	v_lshlrev_b32_e32 v130, 16, v128
	v_lshlrev_b32_e32 v131, 16, v132
	v_and_b32_e32 v128, 0xffff0000, v128
	v_mul_f32_e32 v131, 0xbfb8aa3b, v131
	v_mul_f32_e32 v128, 0xbfb8aa3b, v128
	v_and_b32_e32 v132, 0xffff0000, v132
	v_exp_f32_e32 v131, v131
	v_exp_f32_e32 v128, v128
	v_mul_f32_e32 v132, 0xbfb8aa3b, v132
	v_exp_f32_e32 v132, v132
	v_add_f32_e32 v131, 1.0, v131
	v_add_f32_e32 v128, 1.0, v128
	v_rcp_f32_e32 v134, v131
	v_min_f32_e32 v131, 0x7149f2ca, v128
	v_add_f32_e32 v128, 1.0, v132
	v_lshlrev_b32_e32 v132, 16, v129
	v_and_b32_e32 v133, 0xffff0000, v133
	v_mul_f32_e32 v132, 0xbfb8aa3b, v132
	v_mul_f32_e32 v135, 0xbfb8aa3b, v135
	v_mul_f32_e32 v133, 0xbfb8aa3b, v133
	v_exp_f32_e32 v132, v132
	v_exp_f32_e32 v145, v135
	v_exp_f32_e32 v133, v133
	v_and_b32_e32 v129, 0xffff0000, v129
	v_mul_f32_e32 v129, 0xbfb8aa3b, v129
	v_exp_f32_e32 v129, v129
	v_rcp_f32_e32 v135, v128
	v_add_f32_e32 v128, 1.0, v132
	v_add_f32_e32 v132, 1.0, v145
	v_add_f32_e32 v133, 1.0, v133
	v_rcp_f32_e32 v132, v132
	v_rcp_f32_e32 v133, v133
	v_add_f32_e32 v129, 1.0, v129
	v_min_f32_e32 v128, 0x7149f2ca, v128
	v_min_f32_e32 v129, 0x7149f2ca, v129
	v_pk_mul_f32 v[128:129], v[128:129], v[132:133]
	v_mul_f32_e32 v130, 0xbfb8aa3b, v130
	v_pk_mul_f32 v[90:91], v[90:91], v[128:129]
	v_exp_f32_e32 v130, v130
	v_pk_mul_f32 v[148:149], v[148:149], v[152:153]
	v_add_f32_e32 v130, 1.0, v130
	s_waitcnt vmcnt(1)
	v_lshlrev_b32_e32 v128, 16, v138
	v_mul_f32_e32 v128, 0xbfb8aa3b, v128
	s_waitcnt vmcnt(0)
	v_lshlrev_b32_e32 v129, 16, v142
	v_exp_f32_e32 v128, v128
	v_mul_f32_e32 v129, 0xbfb8aa3b, v129
	v_exp_f32_e32 v129, v129
	v_min_f32_e32 v130, 0x7149f2ca, v130
	v_add_f32_e32 v128, 1.0, v128
	v_pk_mul_f32 v[96:97], v[96:97], v[148:149]
	v_pk_mul_f32 v[130:131], v[130:131], v[134:135]
	v_min_f32_e32 v148, 0x7149f2ca, v128
	v_add_f32_e32 v145, 1.0, v129
	v_and_b32_e32 v132, 0xffff0000, v138
	v_lshl_add_u64 v[128:129], s[6:7], 0, v[150:151]
	v_pk_mul_f32 v[88:89], v[88:89], v[130:131]
	global_load_dwordx4 v[128:131], v[128:129], off
	v_mul_f32_e32 v138, 0xbfb8aa3b, v132
	v_lshl_add_u64 v[132:133], s[70:71], 0, v[150:151]
	global_load_dwordx4 v[132:135], v[132:133], off nt
	v_and_b32_e32 v142, 0xffff0000, v142
	v_exp_f32_e32 v138, v138
	v_mul_f32_e32 v142, 0xbfb8aa3b, v142
	v_exp_f32_e32 v142, v142
	v_rcp_f32_e32 v150, v145
	v_add_f32_e32 v138, 1.0, v138
	v_min_f32_e32 v149, 0x7149f2ca, v138
	v_add_f32_e32 v138, 1.0, v142
	v_lshlrev_b32_e32 v142, 16, v139
	v_lshlrev_b32_e32 v145, 16, v143
	v_and_b32_e32 v143, 0xffff0000, v143
	v_mul_f32_e32 v142, 0xbfb8aa3b, v142
	v_mul_f32_e32 v145, 0xbfb8aa3b, v145
	v_mul_f32_e32 v143, 0xbfb8aa3b, v143
	v_exp_f32_e32 v142, v142
	v_exp_f32_e32 v145, v145
	v_exp_f32_e32 v143, v143
	v_and_b32_e32 v139, 0xffff0000, v139
	v_mul_f32_e32 v139, 0xbfb8aa3b, v139
	v_exp_f32_e32 v139, v139
	v_rcp_f32_e32 v151, v138
	v_add_f32_e32 v138, 1.0, v142
	v_add_f32_e32 v142, 1.0, v145
	v_add_f32_e32 v143, 1.0, v143
	v_rcp_f32_e32 v142, v142
	v_rcp_f32_e32 v143, v143
	v_add_f32_e32 v139, 1.0, v139
	v_min_f32_e32 v138, 0x7149f2ca, v138
	v_min_f32_e32 v139, 0x7149f2ca, v139
	v_pk_mul_f32 v[138:139], v[138:139], v[142:143]
	v_lshlrev_b32_e32 v143, 16, v141
	v_pk_mul_f32 v[86:87], v[86:87], v[138:139]
	v_lshlrev_b32_e32 v138, 16, v136
	v_lshlrev_b32_e32 v139, 16, v140
	v_and_b32_e32 v136, 0xffff0000, v136
	v_mul_f32_e32 v139, 0xbfb8aa3b, v139
	v_mul_f32_e32 v136, 0xbfb8aa3b, v136
	v_and_b32_e32 v140, 0xffff0000, v140
	v_exp_f32_e32 v139, v139
	v_exp_f32_e32 v136, v136
	v_mul_f32_e32 v140, 0xbfb8aa3b, v140
	v_exp_f32_e32 v140, v140
	v_add_f32_e32 v139, 1.0, v139
	v_add_f32_e32 v136, 1.0, v136
	v_rcp_f32_e32 v142, v139
	v_min_f32_e32 v139, 0x7149f2ca, v136
	v_add_f32_e32 v136, 1.0, v140
	v_lshlrev_b32_e32 v140, 16, v137
	v_and_b32_e32 v141, 0xffff0000, v141
	v_mul_f32_e32 v140, 0xbfb8aa3b, v140
	v_mul_f32_e32 v143, 0xbfb8aa3b, v143
	v_mul_f32_e32 v141, 0xbfb8aa3b, v141
	v_exp_f32_e32 v140, v140
	v_exp_f32_e32 v145, v143
	v_exp_f32_e32 v141, v141
	v_and_b32_e32 v137, 0xffff0000, v137
	v_mul_f32_e32 v137, 0xbfb8aa3b, v137
	v_exp_f32_e32 v137, v137
	v_rcp_f32_e32 v143, v136
	v_add_f32_e32 v136, 1.0, v140
	v_add_f32_e32 v140, 1.0, v145
	v_add_f32_e32 v141, 1.0, v141
	v_rcp_f32_e32 v140, v140
	v_rcp_f32_e32 v141, v141
	v_add_f32_e32 v137, 1.0, v137
	v_min_f32_e32 v136, 0x7149f2ca, v136
	v_min_f32_e32 v137, 0x7149f2ca, v137
	v_pk_mul_f32 v[136:137], v[136:137], v[140:141]
	v_mul_f32_e32 v138, 0xbfb8aa3b, v138
	v_pk_mul_f32 v[82:83], v[82:83], v[136:137]
	v_pk_mul_f32 v[148:149], v[148:149], v[150:151]
	v_exp_f32_e32 v138, v138
	v_mov_b32_e32 v145, v147
	v_pk_mul_f32 v[84:85], v[84:85], v[148:149]
	v_add_f32_e32 v138, 1.0, v138
	s_waitcnt vmcnt(1)
	v_lshlrev_b32_e32 v136, 16, v130
	v_mul_f32_e32 v136, 0xbfb8aa3b, v136
	v_exp_f32_e32 v136, v136
	s_waitcnt vmcnt(0)
	v_lshlrev_b32_e32 v137, 16, v134
	v_mul_f32_e32 v137, 0xbfb8aa3b, v137
	v_exp_f32_e32 v137, v137
	v_add_f32_e32 v136, 1.0, v136
	v_min_f32_e32 v148, 0x7149f2ca, v136
	v_min_f32_e32 v138, 0x7149f2ca, v138
	v_add_f32_e32 v149, 1.0, v137
	v_lshlrev_b64 v[136:137], 10, v[144:145]
	v_lshl_add_u64 v[136:137], v[136:137], 0, v[146:147]
	v_lshlrev_b64 v[144:145], 1, v[136:137]
	v_or_b32_e32 v140, 0x100, v144
	v_mov_b32_e32 v141, v145
	v_lshl_add_u64 v[136:137], s[6:7], 0, v[140:141]
	v_lshl_add_u64 v[140:141], s[70:71], 0, v[140:141]
	v_pk_mul_f32 v[138:139], v[138:139], v[142:143]
	global_load_dwordx4 v[140:143], v[140:141], off nt
	v_pk_mul_f32 v[80:81], v[80:81], v[138:139]
	global_load_dwordx4 v[136:139], v[136:137], off
	v_and_b32_e32 v130, 0xffff0000, v130
	v_mul_f32_e32 v130, 0xbfb8aa3b, v130
	v_and_b32_e32 v134, 0xffff0000, v134
	v_exp_f32_e32 v130, v130
	v_mul_f32_e32 v134, 0xbfb8aa3b, v134
	v_exp_f32_e32 v134, v134
	v_rcp_f32_e32 v146, v149
	v_add_f32_e32 v130, 1.0, v130
	v_min_f32_e32 v149, 0x7149f2ca, v130
	v_add_f32_e32 v130, 1.0, v134
	v_lshlrev_b32_e32 v134, 16, v131
	v_lshlrev_b32_e32 v147, 16, v135
	v_and_b32_e32 v135, 0xffff0000, v135
	v_mul_f32_e32 v134, 0xbfb8aa3b, v134
	v_mul_f32_e32 v147, 0xbfb8aa3b, v147
	v_mul_f32_e32 v135, 0xbfb8aa3b, v135
	v_exp_f32_e32 v134, v134
	v_exp_f32_e32 v150, v147
	v_exp_f32_e32 v135, v135
	v_and_b32_e32 v131, 0xffff0000, v131
	v_mul_f32_e32 v131, 0xbfb8aa3b, v131
	v_exp_f32_e32 v131, v131
	v_rcp_f32_e32 v147, v130
	v_add_f32_e32 v130, 1.0, v134
	v_add_f32_e32 v134, 1.0, v150
	v_add_f32_e32 v135, 1.0, v135
	v_rcp_f32_e32 v134, v134
	v_rcp_f32_e32 v135, v135
	v_add_f32_e32 v131, 1.0, v131
	v_min_f32_e32 v130, 0x7149f2ca, v130
	v_min_f32_e32 v131, 0x7149f2ca, v131
	v_pk_mul_f32 v[130:131], v[130:131], v[134:135]
	v_lshlrev_b32_e32 v135, 16, v133
	v_pk_mul_f32 v[70:71], v[70:71], v[130:131]
	v_lshlrev_b32_e32 v130, 16, v128
	v_lshlrev_b32_e32 v131, 16, v132
	v_and_b32_e32 v128, 0xffff0000, v128
	v_mul_f32_e32 v131, 0xbfb8aa3b, v131
	v_mul_f32_e32 v128, 0xbfb8aa3b, v128
	v_and_b32_e32 v132, 0xffff0000, v132
	v_exp_f32_e32 v131, v131
	v_exp_f32_e32 v128, v128
	v_mul_f32_e32 v132, 0xbfb8aa3b, v132
	v_exp_f32_e32 v132, v132
	v_add_f32_e32 v131, 1.0, v131
	v_add_f32_e32 v128, 1.0, v128
	v_rcp_f32_e32 v134, v131
	v_min_f32_e32 v131, 0x7149f2ca, v128
	v_add_f32_e32 v128, 1.0, v132
	v_lshlrev_b32_e32 v132, 16, v129
	v_and_b32_e32 v133, 0xffff0000, v133
	v_pk_mul_f32 v[146:147], v[148:149], v[146:147]
	v_mul_f32_e32 v132, 0xbfb8aa3b, v132
	v_mul_f32_e32 v135, 0xbfb8aa3b, v135
	v_mul_f32_e32 v133, 0xbfb8aa3b, v133
	v_mul_f32_e32 v130, 0xbfb8aa3b, v130
	v_pk_mul_f32 v[68:69], v[68:69], v[146:147]
	v_exp_f32_e32 v132, v132
	v_exp_f32_e32 v146, v135
	v_exp_f32_e32 v133, v133
	v_exp_f32_e32 v130, v130
	v_and_b32_e32 v129, 0xffff0000, v129
	v_mul_f32_e32 v129, 0xbfb8aa3b, v129
	v_rcp_f32_e32 v135, v128
	v_exp_f32_e32 v129, v129
	v_add_f32_e32 v128, 1.0, v132
	v_add_f32_e32 v132, 1.0, v146
	v_add_f32_e32 v133, 1.0, v133
	v_add_f32_e32 v130, 1.0, v130
	v_rcp_f32_e32 v132, v132
	v_rcp_f32_e32 v133, v133
	v_min_f32_e32 v130, 0x7149f2ca, v130
	v_add_f32_e32 v129, 1.0, v129
	v_pk_mul_f32 v[130:131], v[130:131], v[134:135]
	v_min_f32_e32 v128, 0x7149f2ca, v128
	v_min_f32_e32 v129, 0x7149f2ca, v129
	v_pk_mul_f32 v[64:65], v[64:65], v[130:131]
	v_lshl_add_u64 v[130:131], s[6:7], 0, v[144:145]
	v_pk_mul_f32 v[128:129], v[128:129], v[132:133]
	global_load_dwordx4 v[132:135], v[130:131], off
	v_lshl_add_u64 v[130:131], s[70:71], 0, v[144:145]
	global_load_dwordx4 v[144:147], v[130:131], off nt
	v_pk_mul_f32 v[66:67], v[66:67], v[128:129]
	s_waitcnt vmcnt(3)
	v_lshlrev_b32_e32 v129, 16, v142
	s_waitcnt vmcnt(2)
	v_lshlrev_b32_e32 v128, 16, v138
	v_mul_f32_e32 v129, 0xbfb8aa3b, v129
	v_and_b32_e32 v138, 0xffff0000, v138
	v_and_b32_e32 v130, 0xffff0000, v142
	v_exp_f32_e32 v129, v129
	v_mul_f32_e32 v138, 0xbfb8aa3b, v138
	v_mul_f32_e32 v130, 0xbfb8aa3b, v130
	v_exp_f32_e32 v131, v138
	v_exp_f32_e32 v138, v130
	v_lshlrev_b32_e32 v142, 16, v143
	v_and_b32_e32 v143, 0xffff0000, v143
	v_mul_f32_e32 v142, 0xbfb8aa3b, v142
	v_mul_f32_e32 v143, 0xbfb8aa3b, v143
	v_add_f32_e32 v129, 1.0, v129
	v_exp_f32_e32 v142, v142
	v_exp_f32_e32 v143, v143
	v_rcp_f32_e32 v130, v129
	v_add_f32_e32 v129, 1.0, v131
	v_add_f32_e32 v131, 1.0, v138
	v_lshlrev_b32_e32 v138, 16, v139
	v_and_b32_e32 v139, 0xffff0000, v139
	v_mul_f32_e32 v128, 0xbfb8aa3b, v128
	v_mul_f32_e32 v138, 0xbfb8aa3b, v138
	v_mul_f32_e32 v139, 0xbfb8aa3b, v139
	v_exp_f32_e32 v128, v128
	v_exp_f32_e32 v138, v138
	v_exp_f32_e32 v139, v139
	v_add_f32_e32 v142, 1.0, v142
	v_add_f32_e32 v143, 1.0, v143
	v_rcp_f32_e32 v131, v131
	v_rcp_f32_e32 v142, v142
	v_rcp_f32_e32 v143, v143
	v_add_f32_e32 v128, 1.0, v128
	v_add_f32_e32 v138, 1.0, v138
	v_add_f32_e32 v139, 1.0, v139
	v_min_f32_e32 v128, 0x7149f2ca, v128
	v_min_f32_e32 v129, 0x7149f2ca, v129
	v_min_f32_e32 v138, 0x7149f2ca, v138
	v_min_f32_e32 v139, 0x7149f2ca, v139
	v_pk_mul_f32 v[128:129], v[128:129], v[130:131]
	v_pk_mul_f32 v[130:131], v[138:139], v[142:143]
	v_pk_mul_f32 v[56:57], v[56:57], v[128:129]
	v_pk_mul_f32 v[58:59], v[58:59], v[130:131]
	v_lshlrev_b32_e32 v130, 16, v136
	v_mul_f32_e32 v130, 0xbfb8aa3b, v130
	v_exp_f32_e32 v130, v130
	v_lshlrev_b32_e32 v131, 16, v140
	v_mul_f32_e32 v131, 0xbfb8aa3b, v131
	v_exp_f32_e32 v131, v131
	v_add_f32_e32 v128, 1.0, v130
	v_and_b32_e32 v130, 0xffff0000, v136
	v_mul_f32_e32 v130, 0xbfb8aa3b, v130
	v_add_f32_e32 v129, 1.0, v131
	v_exp_f32_e32 v131, v130
	v_and_b32_e32 v130, 0xffff0000, v140
	v_mul_f32_e32 v130, 0xbfb8aa3b, v130
	v_exp_f32_e32 v136, v130
	v_lshlrev_b32_e32 v138, 16, v141
	v_and_b32_e32 v139, 0xffff0000, v141
	v_mul_f32_e32 v138, 0xbfb8aa3b, v138
	v_mul_f32_e32 v139, 0xbfb8aa3b, v139
	v_exp_f32_e32 v138, v138
	v_exp_f32_e32 v139, v139
	v_rcp_f32_e32 v130, v129
	v_add_f32_e32 v129, 1.0, v131
	v_add_f32_e32 v131, 1.0, v136
	v_lshlrev_b32_e32 v136, 16, v137
	v_and_b32_e32 v137, 0xffff0000, v137
	v_mul_f32_e32 v136, 0xbfb8aa3b, v136
	v_mul_f32_e32 v137, 0xbfb8aa3b, v137
	v_exp_f32_e32 v136, v136
	v_exp_f32_e32 v137, v137
	v_add_f32_e32 v138, 1.0, v138
	v_add_f32_e32 v139, 1.0, v139
	v_rcp_f32_e32 v131, v131
	v_rcp_f32_e32 v138, v138
	v_rcp_f32_e32 v139, v139
	v_add_f32_e32 v136, 1.0, v136
	v_add_f32_e32 v137, 1.0, v137
	v_min_f32_e32 v128, 0x7149f2ca, v128
	v_min_f32_e32 v129, 0x7149f2ca, v129
	v_min_f32_e32 v136, 0x7149f2ca, v136
	v_min_f32_e32 v137, 0x7149f2ca, v137
	v_pk_mul_f32 v[128:129], v[128:129], v[130:131]
	v_pk_mul_f32 v[130:131], v[136:137], v[138:139]
	v_pk_mul_f32 v[128:129], v[48:49], v[128:129]
	v_pk_mul_f32 v[130:131], v[50:51], v[130:131]
	s_waitcnt vmcnt(1)
	v_lshlrev_b32_e32 v50, 16, v134
	v_mul_f32_e32 v50, 0xbfb8aa3b, v50
	v_exp_f32_e32 v50, v50
	s_waitcnt vmcnt(0)
	v_lshlrev_b32_e32 v51, 16, v146
	v_mul_f32_e32 v51, 0xbfb8aa3b, v51
	v_exp_f32_e32 v51, v51
	v_add_f32_e32 v48, 1.0, v50
	v_and_b32_e32 v50, 0xffff0000, v134
	v_mul_f32_e32 v50, 0xbfb8aa3b, v50
	v_add_f32_e32 v49, 1.0, v51
	v_exp_f32_e32 v51, v50
	v_and_b32_e32 v50, 0xffff0000, v146
	v_mul_f32_e32 v50, 0xbfb8aa3b, v50
	v_exp_f32_e32 v134, v50
	v_lshlrev_b32_e32 v136, 16, v147
	v_and_b32_e32 v137, 0xffff0000, v147
	v_mul_f32_e32 v136, 0xbfb8aa3b, v136
	v_mul_f32_e32 v137, 0xbfb8aa3b, v137
	v_exp_f32_e32 v136, v136
	v_exp_f32_e32 v137, v137
	v_rcp_f32_e32 v50, v49
	v_add_f32_e32 v49, 1.0, v51
	v_add_f32_e32 v51, 1.0, v134
	v_lshlrev_b32_e32 v134, 16, v135
	v_and_b32_e32 v135, 0xffff0000, v135
	v_mul_f32_e32 v134, 0xbfb8aa3b, v134
	v_mul_f32_e32 v135, 0xbfb8aa3b, v135
	v_exp_f32_e32 v134, v134
	v_exp_f32_e32 v135, v135
	v_add_f32_e32 v136, 1.0, v136
	v_add_f32_e32 v137, 1.0, v137
	v_rcp_f32_e32 v51, v51
	v_rcp_f32_e32 v136, v136
	v_rcp_f32_e32 v137, v137
	v_add_f32_e32 v134, 1.0, v134
	v_add_f32_e32 v135, 1.0, v135
	v_min_f32_e32 v48, 0x7149f2ca, v48
	v_min_f32_e32 v49, 0x7149f2ca, v49
	v_min_f32_e32 v134, 0x7149f2ca, v134
	v_min_f32_e32 v135, 0x7149f2ca, v135
	v_pk_mul_f32 v[48:49], v[48:49], v[50:51]
	v_pk_mul_f32 v[50:51], v[134:135], v[136:137]
	v_pk_mul_f32 v[140:141], v[44:45], v[48:49]
	v_pk_mul_f32 v[142:143], v[46:47], v[50:51]
	v_lshlrev_b32_e32 v46, 16, v132
	v_mul_f32_e32 v46, 0xbfb8aa3b, v46
	v_exp_f32_e32 v46, v46
	v_lshlrev_b32_e32 v47, 16, v144
	v_mul_f32_e32 v47, 0xbfb8aa3b, v47
	v_exp_f32_e32 v47, v47
	v_add_f32_e32 v44, 1.0, v46
	v_and_b32_e32 v46, 0xffff0000, v132
	v_mul_f32_e32 v46, 0xbfb8aa3b, v46
	v_add_f32_e32 v45, 1.0, v47
	v_exp_f32_e32 v47, v46
	v_and_b32_e32 v46, 0xffff0000, v144
	v_mul_f32_e32 v46, 0xbfb8aa3b, v46
	v_exp_f32_e32 v48, v46
	v_lshlrev_b32_e32 v49, 16, v145
	v_mul_f32_e32 v49, 0xbfb8aa3b, v49
	v_and_b32_e32 v51, 0xffff0000, v145
	v_exp_f32_e32 v49, v49
	v_mul_f32_e32 v51, 0xbfb8aa3b, v51
	v_exp_f32_e32 v51, v51
	v_rcp_f32_e32 v46, v45
	v_add_f32_e32 v45, 1.0, v47
	v_add_f32_e32 v47, 1.0, v48
	v_lshlrev_b32_e32 v48, 16, v133
	v_and_b32_e32 v50, 0xffff0000, v133
	v_mul_f32_e32 v48, 0xbfb8aa3b, v48
	v_mul_f32_e32 v50, 0xbfb8aa3b, v50
	v_exp_f32_e32 v48, v48
	v_add_f32_e32 v49, 1.0, v49
	v_exp_f32_e32 v132, v50
	v_rcp_f32_e32 v50, v49
	v_add_f32_e32 v49, 1.0, v51
	v_rcp_f32_e32 v47, v47
	v_rcp_f32_e32 v51, v49
	v_add_f32_e32 v48, 1.0, v48
	v_add_f32_e32 v49, 1.0, v132
	v_min_f32_e32 v44, 0x7149f2ca, v44
	v_min_f32_e32 v45, 0x7149f2ca, v45
	v_min_f32_e32 v48, 0x7149f2ca, v48
	v_min_f32_e32 v49, 0x7149f2ca, v49
	s_waitcnt vmcnt(0)
	v_pk_mul_f32 v[44:45], v[44:45], v[46:47]
	v_pk_mul_f32 v[46:47], v[48:49], v[50:51]
	v_pk_mul_f32 v[148:149], v[40:41], v[44:45]
	v_pk_mul_f32 v[150:151], v[42:43], v[46:47]
	s_barrier
